# v27 + attention loops: K-fragment ds_reads issued right after the tile barrier, ahead of the global prefetch and tile-selection code
# speedup vs baseline: 1.0152x; 1.0052x over previous
; #define ALAS __attribute__((address_space(3)))
; __device__ __forceinline__ void qk_tile(f32x16& s0, f32x16& s1, float ci, const ALAS unsigned char* Kb, const bf16x8 (&qf)[4], int r32, int hi) {
;     const unsigned p0 = (unsigned)(uintptr_t)(Kb + kperm(r32) * ROWB + hi * 16);
;     bf16x8 a[8];
;     ldsr<0>(a[0], p0); ldsr<32 * ROWB>(a[1], p0); ldsr<32>(a[2], p0); ldsr<32 * ROWB + 32>(a[3], p0);
;     ldsr<64>(a[4], p0); ldsr<32 * ROWB + 64>(a[5], p0); ldsr<96>(a[6], p0); ldsr<32 * ROWB + 96>(a[7], p0);
; #pragma unroll
;     for (int r = 0; r < 16; ++r) { s0[r] = ci; s1[r] = ci; }
;     lds_wait8(a); __builtin_amdgcn_sched_barrier(0);
; #pragma unroll
;     for (int d0 = 0; d0 < 4; ++d0) {
;         s0 = __builtin_amdgcn_mfma_f32_32x32x16_bf16(a[2 * d0], qf[d0], s0, 0, 0, 0);
;         s1 = __builtin_amdgcn_mfma_f32_32x32x16_bf16(a[2 * d0 + 1], qf[d0], s1, 0, 0, 0);
;     }
; }
; template <int NDB, int KB>
; __device__ __forceinline__ void issue_v(bf16x8 (&v)[2 * NDB], unsigned vp) {
;     ldsr<0 * 32 * ROWB + 64 * KB>(v[0], vp); ldsr<1 * 32 * ROWB + 64 * KB>(v[1], vp);
;     if constexpr (NDB == 4) { ldsr<2 * 32 * ROWB + 64 * KB>(v[2], vp); ldsr<3 * 32 * ROWB + 64 * KB>(v[3], vp); }
;     ldsr<0 * 32 * ROWB + 64 * KB + 32>(v[NDB + 0], vp); ldsr<1 * 32 * ROWB + 64 * KB + 32>(v[NDB + 1], vp);
; __device__ __forceinline__ void diff_unit(int b, int hd, int qb, const bf16_t* Q, const bf16_t* K, const bf16_t* VT, bf16_t* O, const float* biasd, float lam, const float* subg, ALAS unsigned char* lds) {
;     ...
;     for (int t = 0; t < NT; ++t) {
;         ALAS unsigned char* buf = lds + (t & 1) * 36864;
; #pragma unroll
;         for (int i = 0; i < 2; ++i) { *(ALAS u32x4*)(buf + kl[i]) = kr[i]; *(ALAS u32x4*)(buf + vl[i]) = vr[i]; }
;         __syncthreads();
;         if (t + 1 < NT) {
; #pragma unroll
;             for (int i = 0; i < 2; ++i) { kr[i] = *(const u32x4*)(kg[i] + (size_t)(t + 1) * 64 * 1024); vr[i] = *(const u32x4*)(vg[i] + (t + 1) * 64); }
;         }
;         const int kbase = 64 * t;
;         if (kbase <= q0 + 31) {
;             const bool far = (q0 - (kbase + 63)) >= 128;
;             f32x16 s0, s1; const float ci = (far ? cb : 0.f) - mref;
;             qk_tile(s0, s1, ci, buf + map * 9216, qf, r32, hi);
;             if (!far) near_bias(s0, s1, bt, qpos, kbase, hi);
.LBB0_504:
	s_bitcmp1_b32 s14, 0
	s_cselect_b32 s4, 0, 0x9000
	s_add_i32 s18, s4, 0
	v_add_u32_e32 v64, s18, v138
	s_waitcnt vmcnt(3)
	ds_write_b128 v64, v[112:115]
	v_add_u32_e32 v64, s18, v158
	s_waitcnt vmcnt(1)
	ds_write_b128 v64, v[116:119] offset:18432
	v_add_u32_e32 v64, s18, v142
	s_waitcnt vmcnt(1)
	ds_write_b128 v64, v[120:123]
	v_add_u32_e32 v64, s18, v160
	s_cmp_ge_i32 s14, s16
	s_waitcnt vmcnt(0)
	ds_write_b128 v64, v[124:127] offset:18432
	s_waitcnt lgkmcnt(0)
	s_barrier
	v_add_u32_e32 v144, s18, v139
	v_add3_u32 v144, s11, v144, v130
	ds_read_b128 v[172:175], v144 offset:0
	ds_read_b128 v[176:179], v144 offset:4608
	ds_read_b128 v[180:183], v144 offset:32
	ds_read_b128 v[184:187], v144 offset:4640
	ds_read_b128 v[188:191], v144 offset:64
	ds_read_b128 v[192:195], v144 offset:4672
	ds_read_b128 v[196:199], v144 offset:96
	ds_read_b128 v[216:219], v144 offset:4704
	s_cbranch_scc1 .LBB0_506
	s_add_i32 s4, s17, 64
	s_lshl_b64 s[36:37], s[4:5], 1
	v_lshl_add_u64 v[64:65], v[156:157], 0, s[36:37]
	v_lshl_add_u64 v[66:67], v[140:141], 0, s[36:37]
	global_load_dwordx4 v[112:115], v[164:165], off
	global_load_dwordx4 v[120:123], v[166:167], off
	global_load_dwordx4 v[116:119], v[66:67], off
	global_load_dwordx4 v[124:127], v[64:65], off
.LBB0_506:
	s_cmp_gt_i32 s17, s15
	s_cbranch_scc1 .LBB0_503
	s_cmpk_gt_i32 s12, 0x7f
	s_cselect_b64 vcc, -1, 0
	s_nop 1
	v_cndmask_b32_e32 v64, 0, v137, vcc
	v_sub_f32_e32 v64, v64, v163
	v_mov_b32_e32 v65, v64
	v_mov_b32_e32 v66, v64
	v_mov_b32_e32 v67, v64
	v_mov_b32_e32 v68, v64
	v_mov_b32_e32 v69, v64
	v_mov_b32_e32 v70, v64
	v_mov_b32_e32 v71, v64
	v_mov_b32_e32 v72, v64
	v_mov_b32_e32 v73, v64
	v_mov_b32_e32 v74, v64
	v_mov_b32_e32 v75, v64
	v_mov_b32_e32 v76, v64
	v_mov_b32_e32 v77, v64
	v_mov_b32_e32 v78, v64
	v_mov_b32_e32 v79, v64
	s_waitcnt lgkmcnt(6)
	s_nop 1
	v_mfma_f32_32x32x16_bf16 v[80:95], v[172:175], v[108:111], v[64:79]
	s_and_b64 vcc, exec, vcc
	v_mfma_f32_32x32x16_bf16 v[64:79], v[176:179], v[108:111], v[64:79]
	s_waitcnt lgkmcnt(4)
	v_mfma_f32_32x32x16_bf16 v[80:95], v[180:183], v[104:107], v[80:95]
	v_mfma_f32_32x32x16_bf16 v[64:79], v[184:187], v[104:107], v[64:79]
	s_waitcnt lgkmcnt(2)
	v_mfma_f32_32x32x16_bf16 v[80:95], v[188:191], v[100:103], v[80:95]
	v_mfma_f32_32x32x16_bf16 v[64:79], v[192:195], v[100:103], v[64:79]
	s_waitcnt lgkmcnt(0)
	v_mfma_f32_32x32x16_bf16 v[80:95], v[196:199], v[96:99], v[80:95]
	v_mfma_f32_32x32x16_bf16 v[64:79], v[216:219], v[96:99], v[64:79]
	s_cbranch_vccnz .LBB0_509
	v_add_u32_e32 v161, s12, v159
	v_add_u32_e32 v171, 63, v161
	v_add_u32_e32 v161, 62, v161
	v_med3_i32 v172, v161, 0, v204
	v_lshl_add_u32 v173, v172, 2, s10
	v_max_i32_e32 v172, 32, v161
	v_add_u32_e32 v144, s17, v134
	v_subrev_u32_e32 v172, 32, v172
	v_min_u32_e32 v172, 0xff, v172
	v_or_b32_e32 v175, 2, v144
	v_lshl_add_u32 v174, v172, 2, s10
	v_or_b32_e32 v172, 3, v144
	v_sub_u32_e32 v219, v136, v175
	v_sub_u32_e32 v218, v131, v172
	v_med3_i32 v172, v219, 0, v204
	v_lshl_add_u32 v175, v172, 2, s10
	v_max_i32_e32 v172, 32, v219
	v_subrev_u32_e32 v172, 32, v172
	v_min_u32_e32 v172, 0xff, v172
	v_lshl_add_u32 v176, v172, 2, s10
	v_max_i32_e32 v172, 32, v218
	v_max_i32_e32 v169, 32, v171
	v_subrev_u32_e32 v172, 32, v172
	v_subrev_u32_e32 v169, 32, v169
	v_min_u32_e32 v172, 0xff, v172
	v_med3_i32 v168, v171, 0, v204
	v_min_u32_e32 v169, 0xff, v169
	v_lshl_add_u32 v177, v172, 2, s10
	v_med3_i32 v172, v218, 0, v204
	v_lshl_add_u32 v168, v168, 2, s10
	v_lshl_add_u32 v169, v169, 2, s10
	v_lshl_add_u32 v178, v172, 2, s10
	ds_read_b32 v172, v168
	ds_read_b32 v168, v169
	ds_read_b32 v173, v173
	ds_read_b32 v169, v174
	ds_read_b32 v174, v175
	ds_read_b32 v176, v176
	ds_read_b32 v177, v177
	ds_read_b32 v175, v178
	v_or_b32_e32 v178, 5, v144
	v_sub_u32_e32 v220, v131, v178
	v_max_i32_e32 v180, 32, v220
	v_subrev_u32_e32 v180, 32, v180
	v_min_u32_e32 v180, 0xff, v180
	v_lshl_add_u32 v181, v180, 2, s10
	v_med3_i32 v180, v220, 0, v204
	v_or_b32_e32 v183, 6, v144
	v_lshl_add_u32 v182, v180, 2, s10
	v_or_b32_e32 v180, 7, v144
	v_sub_u32_e32 v223, v136, v183
	v_sub_u32_e32 v222, v131, v180
	v_med3_i32 v180, v223, 0, v204
	v_lshl_add_u32 v183, v180, 2, s10
	v_max_i32_e32 v180, 32, v223
	v_subrev_u32_e32 v180, 32, v180
	v_or_b32_e32 v179, 4, v144
	v_min_u32_e32 v180, 0xff, v180
	v_sub_u32_e32 v221, v136, v179
	v_lshl_add_u32 v184, v180, 2, s10
	v_max_i32_e32 v180, 32, v222
	v_max_i32_e32 v179, 32, v221
	v_subrev_u32_e32 v180, 32, v180
	v_subrev_u32_e32 v179, 32, v179
	v_min_u32_e32 v180, 0xff, v180
	v_med3_i32 v178, v221, 0, v204
	v_min_u32_e32 v179, 0xff, v179
	v_lshl_add_u32 v185, v180, 2, s10
	v_med3_i32 v180, v222, 0, v204
	v_lshl_add_u32 v178, v178, 2, s10
	v_lshl_add_u32 v179, v179, 2, s10
	v_lshl_add_u32 v186, v180, 2, s10
	ds_read_b32 v178, v178
	ds_read_b32 v180, v179
	ds_read_b32 v181, v181
	ds_read_b32 v179, v182
	ds_read_b32 v182, v183
	ds_read_b32 v184, v184
	ds_read_b32 v185, v185
	ds_read_b32 v183, v186
	v_or_b32_e32 v186, 17, v144
	v_sub_u32_e32 v224, v131, v186
	v_max_i32_e32 v188, 32, v224
	v_subrev_u32_e32 v188, 32, v188
	v_min_u32_e32 v188, 0xff, v188
	v_lshl_add_u32 v189, v188, 2, s10
	v_med3_i32 v188, v224, 0, v204
	v_or_b32_e32 v191, 18, v144
	v_lshl_add_u32 v190, v188, 2, s10
	v_or_b32_e32 v188, 19, v144
	v_sub_u32_e32 v227, v136, v191
	v_sub_u32_e32 v226, v131, v188
; #define ALAS __attribute__((address_space(3)))
; __device__ __forceinline__ void near_bias(f32x16& s0, f32x16& s1, const ALAS float* bt, int qpos, int kbase, int hi) {
; #pragma unroll
;     for (int r = 0; r < 16; ++r) {
;         const int d0 = qpos - (kbase + (r & 7) + 8 * hi + 16 * (r >> 3)), d1 = d0 - 32;
;         const float b0 = bt[min(max(d0, 0), 255)], b1 = bt[min(max(d1, 0), 255)];
;         s0[r] = d0 < 0 ? NEG : s0[r] + b0; s1[r] = d1 < 0 ? NEG : s1[r] + b1;
;     }
; }
	v_med3_i32 v188, v227, 0, v204
	v_lshl_add_u32 v191, v188, 2, s10
	v_max_i32_e32 v188, 32, v227
	v_subrev_u32_e32 v188, 32, v188
	v_or_b32_e32 v187, 16, v144
	v_min_u32_e32 v188, 0xff, v188
	v_sub_u32_e32 v225, v136, v187
	v_lshl_add_u32 v192, v188, 2, s10
	v_max_i32_e32 v188, 32, v226
	v_max_i32_e32 v187, 32, v225
	v_subrev_u32_e32 v188, 32, v188
	v_subrev_u32_e32 v187, 32, v187
	v_min_u32_e32 v188, 0xff, v188
	v_med3_i32 v186, v225, 0, v204
	v_min_u32_e32 v187, 0xff, v187
	v_lshl_add_u32 v193, v188, 2, s10
	v_med3_i32 v188, v226, 0, v204
	v_lshl_add_u32 v186, v186, 2, s10
	v_lshl_add_u32 v187, v187, 2, s10
	v_lshl_add_u32 v194, v188, 2, s10
	ds_read_b32 v186, v186
	ds_read_b32 v188, v187
	ds_read_b32 v189, v189
	ds_read_b32 v187, v190
	ds_read_b32 v190, v191
	ds_read_b32 v192, v192
	ds_read_b32 v193, v193
	ds_read_b32 v191, v194
	v_or_b32_e32 v194, 21, v144
	v_sub_u32_e32 v228, v131, v194
	v_max_i32_e32 v196, 32, v228
	v_subrev_u32_e32 v196, 32, v196
	v_min_u32_e32 v196, 0xff, v196
	v_lshl_add_u32 v197, v196, 2, s10
	v_med3_i32 v196, v228, 0, v204
	v_or_b32_e32 v195, 20, v144
	v_lshl_add_u32 v198, v196, 2, s10
	v_or_b32_e32 v196, 23, v144
	v_or_b32_e32 v144, 22, v144
	v_sub_u32_e32 v144, v136, v144
	v_sub_u32_e32 v230, v131, v196
	v_med3_i32 v196, v144, 0, v204
	v_lshl_add_u32 v199, v196, 2, s10
	v_max_i32_e32 v196, 32, v144
	v_subrev_u32_e32 v196, 32, v196
	v_sub_u32_e32 v229, v136, v195
	v_min_u32_e32 v196, 0xff, v196
	v_max_i32_e32 v195, 32, v229
	v_lshl_add_u32 v216, v196, 2, s10
	v_max_i32_e32 v196, 32, v230
	v_subrev_u32_e32 v195, 32, v195
	v_subrev_u32_e32 v196, 32, v196
	v_med3_i32 v194, v229, 0, v204
	v_min_u32_e32 v195, 0xff, v195
	v_min_u32_e32 v196, 0xff, v196
	v_lshl_add_u32 v194, v194, 2, s10
	v_lshl_add_u32 v195, v195, 2, s10
	v_lshl_add_u32 v217, v196, 2, s10
	v_med3_i32 v196, v230, 0, v204
	v_lshl_add_u32 v231, v196, 2, s10
	ds_read_b32 v194, v194
	ds_read_b32 v196, v195
	ds_read_b32 v197, v197
	ds_read_b32 v195, v198
	ds_read_b32 v198, v199
	ds_read_b32 v216, v216
	ds_read_b32 v217, v217
	ds_read_b32 v199, v231
	v_cmp_lt_i32_e32 vcc, -1, v230
	s_waitcnt lgkmcnt(4)
	v_pk_add_f32 v[92:93], v[92:93], v[194:195]
	v_pk_add_f32 v[90:91], v[90:91], v[190:191]
	v_pk_add_f32 v[88:89], v[88:89], v[186:187]
	s_waitcnt lgkmcnt(0)
	v_pk_add_f32 v[94:95], v[94:95], v[198:199]
	v_pk_add_f32 v[86:87], v[86:87], v[182:183]
	v_cndmask_b32_e32 v95, v205, v95, vcc
	v_cmp_lt_i32_e32 vcc, -1, v144
	v_pk_add_f32 v[84:85], v[84:85], v[178:179]
	v_pk_add_f32 v[82:83], v[82:83], v[174:175]
	v_cndmask_b32_e32 v94, v205, v94, vcc
	v_cmp_lt_i32_e32 vcc, -1, v228
	v_pk_add_f32 v[80:81], v[80:81], v[172:173]
	v_pk_add_f32 v[78:79], v[78:79], v[216:217]
	v_cndmask_b32_e32 v93, v205, v93, vcc
	v_cmp_lt_i32_e32 vcc, -1, v229
	v_pk_add_f32 v[76:77], v[76:77], v[196:197]
	v_pk_add_f32 v[74:75], v[74:75], v[192:193]
	v_cndmask_b32_e32 v92, v205, v92, vcc
	v_cmp_lt_i32_e32 vcc, -1, v226
	v_pk_add_f32 v[72:73], v[72:73], v[188:189]
	v_pk_add_f32 v[70:71], v[70:71], v[184:185]
	v_cndmask_b32_e32 v91, v205, v91, vcc
	v_cmp_lt_i32_e32 vcc, -1, v227
	v_pk_add_f32 v[68:69], v[68:69], v[180:181]
	v_pk_add_f32 v[66:67], v[66:67], v[176:177]
	v_cndmask_b32_e32 v90, v205, v90, vcc
	v_cmp_lt_i32_e32 vcc, -1, v224
	v_pk_add_f32 v[64:65], v[64:65], v[168:169]
	s_nop 0
	v_cndmask_b32_e32 v89, v205, v89, vcc
	v_cmp_lt_i32_e32 vcc, -1, v225
	s_nop 1
	v_cndmask_b32_e32 v88, v205, v88, vcc
	v_cmp_lt_i32_e32 vcc, -1, v222
	s_nop 1
	v_cndmask_b32_e32 v87, v205, v87, vcc
	v_cmp_lt_i32_e32 vcc, -1, v223
	s_nop 1
	v_cndmask_b32_e32 v86, v205, v86, vcc
	v_cmp_lt_i32_e32 vcc, -1, v220
	s_nop 1
	v_cndmask_b32_e32 v85, v205, v85, vcc
	v_cmp_lt_i32_e32 vcc, -1, v221
	s_nop 1
	v_cndmask_b32_e32 v84, v205, v84, vcc
	v_cmp_lt_i32_e32 vcc, -1, v218
	s_nop 1
	v_cndmask_b32_e32 v83, v205, v83, vcc
	v_cmp_lt_i32_e32 vcc, -1, v219
	s_nop 1
	v_cndmask_b32_e32 v82, v205, v82, vcc
	v_cmp_lt_i32_e32 vcc, -1, v161
	s_nop 1
	v_cndmask_b32_e32 v81, v205, v81, vcc
	v_cmp_lt_i32_e32 vcc, -1, v171
	s_nop 1
	v_cndmask_b32_e32 v80, v205, v80, vcc
	v_cmp_lt_i32_e32 vcc, 31, v230
	s_nop 1
	v_cndmask_b32_e32 v79, v205, v79, vcc
	v_cmp_lt_i32_e32 vcc, 31, v144
	s_nop 1
	v_cndmask_b32_e32 v78, v205, v78, vcc
	v_cmp_lt_i32_e32 vcc, 31, v228
	s_nop 1
	v_cndmask_b32_e32 v77, v205, v77, vcc
	v_cmp_lt_i32_e32 vcc, 31, v229
	s_nop 1
	v_cndmask_b32_e32 v76, v205, v76, vcc
	v_cmp_lt_i32_e32 vcc, 31, v226
	s_nop 1
	v_cndmask_b32_e32 v75, v205, v75, vcc
	v_cmp_lt_i32_e32 vcc, 31, v227
	s_nop 1
	v_cndmask_b32_e32 v74, v205, v74, vcc
	v_cmp_lt_i32_e32 vcc, 31, v224
	s_nop 1
	v_cndmask_b32_e32 v73, v205, v73, vcc
	v_cmp_lt_i32_e32 vcc, 31, v225
	s_nop 1
	v_cndmask_b32_e32 v72, v205, v72, vcc
	v_cmp_lt_i32_e32 vcc, 31, v222
	s_nop 1
	v_cndmask_b32_e32 v71, v205, v71, vcc
	v_cmp_lt_i32_e32 vcc, 31, v223
	s_nop 1
	v_cndmask_b32_e32 v70, v205, v70, vcc
	v_cmp_lt_i32_e32 vcc, 31, v220
	s_nop 1
	v_cndmask_b32_e32 v69, v205, v69, vcc
	v_cmp_lt_i32_e32 vcc, 31, v221
	s_nop 1
	v_cndmask_b32_e32 v68, v205, v68, vcc
	v_cmp_lt_i32_e32 vcc, 31, v218
	s_nop 1
	v_cndmask_b32_e32 v67, v205, v67, vcc
	v_cmp_lt_i32_e32 vcc, 31, v219
	s_nop 1
	v_cndmask_b32_e32 v66, v205, v66, vcc
	v_cmp_lt_i32_e32 vcc, 31, v161
	s_nop 1
	v_cndmask_b32_e32 v65, v205, v65, vcc
	v_cmp_lt_i32_e32 vcc, 31, v171
	s_nop 1
	v_cndmask_b32_e32 v64, v205, v64, vcc

; #define ALAS __attribute__((address_space(3)))
; __device__ __forceinline__ int kperm(int i) { return (i & 19) | ((i & 4) << 1) | ((i & 8) >> 1); }
; template <int OFF> __device__ __forceinline__ void ldsr(bf16x8& d, unsigned a) { asm volatile("ds_read_b128 %0, %1 offset:%c2" : "=v"(d) : "v"(a), "i"(OFF) : "memory"); }
; __device__ __forceinline__ void qk_tile(f32x16& s0, f32x16& s1, float ci, const ALAS unsigned char* Kb, const bf16x8 (&qf)[4], int r32, int hi) {
;     const unsigned p0 = (unsigned)(uintptr_t)(Kb + kperm(r32) * ROWB + hi * 16);
;     bf16x8 a[8];
;     ldsr<0>(a[0], p0); ldsr<32 * ROWB>(a[1], p0); ldsr<32>(a[2], p0); ldsr<32 * ROWB + 32>(a[3], p0);
;     ldsr<64>(a[4], p0); ldsr<32 * ROWB + 64>(a[5], p0); ldsr<96>(a[6], p0); ldsr<32 * ROWB + 96>(a[7], p0);
; __device__ __forceinline__ void moba_unit(int b, int h, int j, const bf16_t* Q, const bf16_t* K, const bf16_t* VT, bf16_t* O, const float* biasd, const float* kmean, ALAS unsigned char* lds) {
;     ...
;     for (int t = 0; t < NT; ++t) {
;         ALAS unsigned char* buf = lds + (t & 1) * 18432;
;         *(ALAS u32x4*)(buf + kl) = kr; *(ALAS u32x4*)(buf + vl) = vr;
;         __syncthreads();
;         if (t + 1 < NT) { const int t1 = t + 1; const int kb1 = (t1 < 4) ? (256 * j + 64 * t1) : (64 * (t1 - 4));
;             kr = *(const u32x4*)(kg + (size_t)kb1 * 1024); vr = *(const u32x4*)(vg + kb1); }
.LBB0_533:
	s_add_i32 s8, s16, 4
	s_bitcmp1_b32 s8, 0
	s_cselect_b32 s0, 0x4800, 0
	s_add_i32 s17, s0, 0
	s_add_i32 s0, s16, 5
	v_add3_u32 v32, s17, v104, v92
	s_cmp_lt_i32 s0, s14
	s_mov_b64 s[0:1], -1
	s_waitcnt vmcnt(1)
	ds_write_b128 v32, v[80:83]
	s_waitcnt vmcnt(0)
	ds_write_b128 v32, v[84:87] offset:9216
	s_waitcnt lgkmcnt(0)
	s_barrier
	v_add3_u32 v216, s17, v105, v144
	ds_read_b128 v[108:111], v216 offset:0
	ds_read_b128 v[112:115], v216 offset:4608
	ds_read_b128 v[116:119], v216 offset:32
	ds_read_b128 v[120:123], v216 offset:4640
	ds_read_b128 v[124:127], v216 offset:64
	ds_read_b128 v[128:131], v216 offset:4672
	ds_read_b128 v[132:135], v216 offset:96
	ds_read_b128 v[136:139], v216 offset:4704
	s_cbranch_scc1 .LBB0_535
	s_add_i32 s18, s96, s15
	s_mov_b64 s[0:1], 0

; __device__ __forceinline__ void qk_tile(f32x16& s0, f32x16& s1, float ci, const ALAS unsigned char* Kb, const bf16x8 (&qf)[4], int r32, int hi) {
;     const unsigned p0 = (unsigned)(uintptr_t)(Kb + kperm(r32) * ROWB + hi * 16);
;     bf16x8 a[8];
;     ldsr<0>(a[0], p0); ldsr<32 * ROWB>(a[1], p0); ldsr<32>(a[2], p0); ldsr<32 * ROWB + 32>(a[3], p0);
;     ldsr<64>(a[4], p0); ldsr<32 * ROWB + 64>(a[5], p0); ldsr<96>(a[6], p0); ldsr<32 * ROWB + 96>(a[7], p0);
; #pragma unroll
;     for (int r = 0; r < 16; ++r) { s0[r] = ci; s1[r] = ci; }
;     lds_wait8(a); __builtin_amdgcn_sched_barrier(0);
; #pragma unroll
;     for (int d0 = 0; d0 < 4; ++d0) {
;         s0 = __builtin_amdgcn_mfma_f32_32x32x16_bf16(a[2 * d0], qf[d0], s0, 0, 0, 0);
;         s1 = __builtin_amdgcn_mfma_f32_32x32x16_bf16(a[2 * d0 + 1], qf[d0], s1, 0, 0, 0);
;     }
; }
; template <int NDB, int KB>
; __device__ __forceinline__ void issue_v(bf16x8 (&v)[2 * NDB], unsigned vp) {
;     ldsr<0 * 32 * ROWB + 64 * KB>(v[0], vp); ldsr<1 * 32 * ROWB + 64 * KB>(v[1], vp);
;     if constexpr (NDB == 4) { ldsr<2 * 32 * ROWB + 64 * KB>(v[2], vp); ldsr<3 * 32 * ROWB + 64 * KB>(v[3], vp); }
;     ldsr<0 * 32 * ROWB + 64 * KB + 32>(v[NDB + 0], vp); ldsr<1 * 32 * ROWB + 64 * KB + 32>(v[NDB + 1], vp);
;     if constexpr (NDB == 4) { ldsr<2 * 32 * ROWB + 64 * KB + 32>(v[NDB + 2], vp); ldsr<3 * 32 * ROWB + 64 * KB + 32>(v[NDB + 3], vp); }
; }
; __device__ __forceinline__ void pack16(const f32x16& s, bf16x8& pf0, bf16x8& pf1) {
;     u32x4 w0, w1;
;     w0.x = cvtpk(s[0], s[1]); w0.y = cvtpk(s[2], s[3]); w0.z = cvtpk(s[4], s[5]); w0.w = cvtpk(s[6], s[7]);
; __device__ __forceinline__ void moba_unit(int b, int h, int j, const bf16_t* Q, const bf16_t* K, const bf16_t* VT, bf16_t* O, const float* biasd, const float* kmean, ALAS unsigned char* lds) {
;     ...
;         const bool own = t < 4; const int n = own ? j : ((t - 4) >> 2); const int kbase = own ? (256 * j + 64 * t) : (64 * (t - 4));
;         const bool sel = own ? true : (((selmask >> n) & 1u) != 0u);
;         const bool active = own ? (64 * t <= 32 * wid + 31) : (__any(sel) != 0);
;         if (active) {
;             const bool nearb = (q0 - (kbase + 63)) < 128;
;             f32x16 s0, s1; const float ci = sel ? ((nearb ? 0.f : cb) - mref) : NEG;
;             qk_tile(s0, s1, ci, buf, qf, r32, hi);
;             if (nearb) near_bias(s0, s1, bt, qpos, kbase, hi);
.LBB0_542:
	s_add_i32 s10, s18, 0x100
	s_and_b64 s[8:9], s[6:7], exec
	s_cselect_b32 s8, s10, s15
	s_or_b64 vcc, s[6:7], s[0:1]
	s_sub_i32 s0, s4, s8
	s_cmpk_gt_i32 s0, 0x7f
	s_cselect_b64 s[0:1], -1, 0
	v_cndmask_b32_e64 v32, 0, v99, s[0:1]
	v_sub_f32_e32 v32, v32, v101
	v_cndmask_b32_e32 v32, v205, v32, vcc
	v_mov_b32_e32 v33, v32
	v_mov_b32_e32 v34, v32
	v_mov_b32_e32 v35, v32
	v_mov_b32_e32 v36, v32
	v_mov_b32_e32 v37, v32
	v_mov_b32_e32 v38, v32
	v_mov_b32_e32 v39, v32
	v_mov_b32_e32 v40, v32
	v_mov_b32_e32 v41, v32
	v_mov_b32_e32 v42, v32
	v_mov_b32_e32 v43, v32
	v_mov_b32_e32 v44, v32
	v_mov_b32_e32 v45, v32
	v_mov_b32_e32 v46, v32
	v_mov_b32_e32 v47, v32
	s_waitcnt lgkmcnt(6)
	s_nop 1
	v_mfma_f32_32x32x16_bf16 v[48:63], v[108:111], v[64:67], v[32:47]
	s_and_b64 vcc, exec, s[0:1]
	v_mfma_f32_32x32x16_bf16 v[32:47], v[112:115], v[64:67], v[32:47]
	s_waitcnt lgkmcnt(4)
	v_mfma_f32_32x32x16_bf16 v[48:63], v[116:119], v[68:71], v[48:63]
	v_mfma_f32_32x32x16_bf16 v[32:47], v[120:123], v[68:71], v[32:47]
	s_waitcnt lgkmcnt(2)
	v_mfma_f32_32x32x16_bf16 v[48:63], v[124:127], v[72:75], v[48:63]
	v_mfma_f32_32x32x16_bf16 v[32:47], v[128:131], v[72:75], v[32:47]
	s_waitcnt lgkmcnt(0)
	v_mfma_f32_32x32x16_bf16 v[48:63], v[132:135], v[76:79], v[48:63]
	v_mfma_f32_32x32x16_bf16 v[32:47], v[136:139], v[76:79], v[32:47]
	s_cbranch_vccnz .LBB0_544
	v_or_b32_e32 v130, s8, v98
	v_xad_u32 v139, v130, -1, v90
	v_med3_i32 v108, v139, 0, v204
	v_lshl_add_u32 v109, v108, 2, 0
	v_max_i32_e32 v108, 32, v139
	v_subrev_u32_e32 v108, 32, v108
	v_min_u32_e32 v108, 0xff, v108
	v_or_b32_e32 v111, 2, v130
	v_lshl_add_u32 v110, v108, 2, 0
	v_or_b32_e32 v108, 3, v130
	v_sub_u32_e32 v141, v90, v111
	v_sub_u32_e32 v140, v91, v108
	v_med3_i32 v108, v141, 0, v204
	v_lshl_add_u32 v111, v108, 2, 0
	v_max_i32_e32 v108, 32, v141
	v_subrev_u32_e32 v108, 32, v108
	v_min_u32_e32 v108, 0xff, v108
	v_sub_u32_e32 v138, v90, v130
	v_lshl_add_u32 v112, v108, 2, 0
	v_max_i32_e32 v108, 32, v140
	v_max_i32_e32 v103, 32, v138
	v_subrev_u32_e32 v108, 32, v108
	v_subrev_u32_e32 v103, 32, v103
	v_min_u32_e32 v108, 0xff, v108
	v_med3_i32 v102, v138, 0, v204
	v_min_u32_e32 v103, 0xff, v103
	v_lshl_add_u32 v113, v108, 2, 0
	v_med3_i32 v108, v140, 0, v204
	v_lshl_add_u32 v102, v102, 2, 0
	v_lshl_add_u32 v103, v103, 2, 0
	v_lshl_add_u32 v114, v108, 2, 0
	ds_read_b32 v108, v102 offset:36864
	ds_read_b32 v102, v103 offset:36864
	ds_read_b32 v109, v109 offset:36864
	ds_read_b32 v103, v110 offset:36864
	ds_read_b32 v110, v111 offset:36864
	ds_read_b32 v112, v112 offset:36864
	ds_read_b32 v113, v113 offset:36864
	ds_read_b32 v111, v114 offset:36864
	v_or_b32_e32 v114, 5, v130
	v_sub_u32_e32 v142, v91, v114
	v_max_i32_e32 v116, 32, v142
	v_subrev_u32_e32 v116, 32, v116
	v_min_u32_e32 v116, 0xff, v116
	v_lshl_add_u32 v117, v116, 2, 0
	v_med3_i32 v116, v142, 0, v204
	v_or_b32_e32 v119, 6, v130
	v_lshl_add_u32 v118, v116, 2, 0
	v_or_b32_e32 v116, 7, v130
	v_sub_u32_e32 v157, v90, v119
	v_sub_u32_e32 v156, v91, v116
	v_med3_i32 v116, v157, 0, v204
	v_lshl_add_u32 v119, v116, 2, 0
	v_max_i32_e32 v116, 32, v157
	v_subrev_u32_e32 v116, 32, v116
	v_or_b32_e32 v115, 4, v130
	v_min_u32_e32 v116, 0xff, v116
	v_sub_u32_e32 v143, v90, v115
	v_lshl_add_u32 v120, v116, 2, 0
	v_max_i32_e32 v116, 32, v156
	v_max_i32_e32 v115, 32, v143
	v_subrev_u32_e32 v116, 32, v116
	v_subrev_u32_e32 v115, 32, v115
	v_min_u32_e32 v116, 0xff, v116
	v_med3_i32 v114, v143, 0, v204
	v_min_u32_e32 v115, 0xff, v115
	v_lshl_add_u32 v121, v116, 2, 0
	v_med3_i32 v116, v156, 0, v204
	v_lshl_add_u32 v114, v114, 2, 0
	v_lshl_add_u32 v115, v115, 2, 0
	v_lshl_add_u32 v122, v116, 2, 0
	ds_read_b32 v114, v114 offset:36864
	ds_read_b32 v116, v115 offset:36864
	ds_read_b32 v117, v117 offset:36864
	ds_read_b32 v115, v118 offset:36864
	ds_read_b32 v118, v119 offset:36864
	ds_read_b32 v120, v120 offset:36864
	ds_read_b32 v121, v121 offset:36864
	ds_read_b32 v119, v122 offset:36864
	v_or_b32_e32 v122, 17, v130
	v_sub_u32_e32 v158, v91, v122
	v_max_i32_e32 v124, 32, v158
	v_subrev_u32_e32 v124, 32, v124
	v_min_u32_e32 v124, 0xff, v124
	v_lshl_add_u32 v125, v124, 2, 0
	v_med3_i32 v124, v158, 0, v204
	v_or_b32_e32 v127, 18, v130
	v_lshl_add_u32 v126, v124, 2, 0
	v_or_b32_e32 v124, 19, v130
	v_sub_u32_e32 v161, v90, v127
	v_sub_u32_e32 v160, v91, v124
	v_med3_i32 v124, v161, 0, v204
	v_lshl_add_u32 v127, v124, 2, 0
	v_max_i32_e32 v124, 32, v161
	v_subrev_u32_e32 v124, 32, v124
	v_or_b32_e32 v123, 16, v130
	v_min_u32_e32 v124, 0xff, v124
	v_sub_u32_e32 v159, v90, v123
	v_lshl_add_u32 v128, v124, 2, 0
	v_max_i32_e32 v124, 32, v160
	v_max_i32_e32 v123, 32, v159
	v_subrev_u32_e32 v124, 32, v124
	v_subrev_u32_e32 v123, 32, v123
	v_min_u32_e32 v124, 0xff, v124
	v_med3_i32 v122, v159, 0, v204
	v_min_u32_e32 v123, 0xff, v123
	v_lshl_add_u32 v129, v124, 2, 0
	v_med3_i32 v124, v160, 0, v204
	v_lshl_add_u32 v122, v122, 2, 0
	v_lshl_add_u32 v123, v123, 2, 0
	v_lshl_add_u32 v131, v124, 2, 0
	ds_read_b32 v122, v122 offset:36864
	ds_read_b32 v124, v123 offset:36864
	ds_read_b32 v125, v125 offset:36864
	ds_read_b32 v123, v126 offset:36864
	ds_read_b32 v126, v127 offset:36864
	ds_read_b32 v128, v128 offset:36864
	ds_read_b32 v129, v129 offset:36864
	ds_read_b32 v127, v131 offset:36864
	v_or_b32_e32 v131, 21, v130
	v_or_b32_e32 v132, 20, v130
	v_or_b32_e32 v135, 23, v130
	v_or_b32_e32 v130, 22, v130
	v_sub_u32_e32 v165, v90, v130
	v_med3_i32 v130, v165, 0, v204
	v_sub_u32_e32 v164, v91, v135
	v_lshl_add_u32 v135, v130, 2, 0
	v_max_i32_e32 v130, 32, v165
	v_subrev_u32_e32 v130, 32, v130
	v_sub_u32_e32 v162, v91, v131
	v_sub_u32_e32 v163, v90, v132
	v_min_u32_e32 v130, 0xff, v130
	v_max_i32_e32 v132, 32, v163
	v_max_i32_e32 v133, 32, v162
	v_lshl_add_u32 v136, v130, 2, 0
	v_max_i32_e32 v130, 32, v164
	v_subrev_u32_e32 v132, 32, v132
	v_subrev_u32_e32 v133, 32, v133
	v_subrev_u32_e32 v130, 32, v130
	v_med3_i32 v131, v163, 0, v204
	v_min_u32_e32 v132, 0xff, v132
	v_min_u32_e32 v133, 0xff, v133
	v_med3_i32 v134, v162, 0, v204
	v_min_u32_e32 v130, 0xff, v130
	v_lshl_add_u32 v131, v131, 2, 0
	v_lshl_add_u32 v132, v132, 2, 0
	v_lshl_add_u32 v133, v133, 2, 0
	v_lshl_add_u32 v134, v134, 2, 0
	v_lshl_add_u32 v137, v130, 2, 0
	v_med3_i32 v130, v164, 0, v204
	v_lshl_add_u32 v166, v130, 2, 0
	ds_read_b32 v130, v131 offset:36864
	ds_read_b32 v132, v132 offset:36864
	ds_read_b32 v133, v133 offset:36864
	ds_read_b32 v131, v134 offset:36864
	ds_read_b32 v134, v135 offset:36864
	ds_read_b32 v136, v136 offset:36864
	ds_read_b32 v137, v137 offset:36864
	ds_read_b32 v135, v166 offset:36864
	v_cmp_lt_i32_e32 vcc, -1, v164
	s_waitcnt lgkmcnt(4)
; #define ALAS __attribute__((address_space(3)))
; __device__ __forceinline__ void near_bias(f32x16& s0, f32x16& s1, const ALAS float* bt, int qpos, int kbase, int hi) {
; #pragma unroll
;     for (int r = 0; r < 16; ++r) {
;         const int d0 = qpos - (kbase + (r & 7) + 8 * hi + 16 * (r >> 3)), d1 = d0 - 32;
;         const float b0 = bt[min(max(d0, 0), 255)], b1 = bt[min(max(d1, 0), 255)];
;         s0[r] = d0 < 0 ? NEG : s0[r] + b0; s1[r] = d1 < 0 ? NEG : s1[r] + b1;
;     }
; }
	v_pk_add_f32 v[60:61], v[60:61], v[130:131]
	v_pk_add_f32 v[58:59], v[58:59], v[126:127]
	v_pk_add_f32 v[56:57], v[56:57], v[122:123]
	s_waitcnt lgkmcnt(0)
	v_pk_add_f32 v[62:63], v[62:63], v[134:135]
	v_pk_add_f32 v[54:55], v[54:55], v[118:119]
	v_cndmask_b32_e32 v63, v205, v63, vcc
	v_cmp_lt_i32_e32 vcc, -1, v165
	v_pk_add_f32 v[52:53], v[52:53], v[114:115]
	v_pk_add_f32 v[50:51], v[50:51], v[110:111]
	v_cndmask_b32_e32 v62, v205, v62, vcc
	v_cmp_lt_i32_e32 vcc, -1, v162
	v_pk_add_f32 v[48:49], v[48:49], v[108:109]
	v_pk_add_f32 v[46:47], v[46:47], v[136:137]
	v_cndmask_b32_e32 v61, v205, v61, vcc
	v_cmp_lt_i32_e32 vcc, -1, v163
	v_pk_add_f32 v[44:45], v[44:45], v[132:133]
	v_pk_add_f32 v[42:43], v[42:43], v[128:129]
	v_cndmask_b32_e32 v60, v205, v60, vcc
	v_cmp_lt_i32_e32 vcc, -1, v160
	v_pk_add_f32 v[40:41], v[40:41], v[124:125]
	v_pk_add_f32 v[38:39], v[38:39], v[120:121]
	v_cndmask_b32_e32 v59, v205, v59, vcc
	v_cmp_lt_i32_e32 vcc, -1, v161
	v_pk_add_f32 v[36:37], v[36:37], v[116:117]
	v_pk_add_f32 v[34:35], v[34:35], v[112:113]
	v_cndmask_b32_e32 v58, v205, v58, vcc
	v_cmp_lt_i32_e32 vcc, -1, v158
	v_pk_add_f32 v[32:33], v[32:33], v[102:103]
	s_nop 0
	v_cndmask_b32_e32 v57, v205, v57, vcc
	v_cmp_lt_i32_e32 vcc, -1, v159
	s_nop 1
	v_cndmask_b32_e32 v56, v205, v56, vcc
	v_cmp_lt_i32_e32 vcc, -1, v156
	s_nop 1
	v_cndmask_b32_e32 v55, v205, v55, vcc
	v_cmp_lt_i32_e32 vcc, -1, v157
	s_nop 1
	v_cndmask_b32_e32 v54, v205, v54, vcc
	v_cmp_lt_i32_e32 vcc, -1, v142
	s_nop 1
	v_cndmask_b32_e32 v53, v205, v53, vcc
	v_cmp_lt_i32_e32 vcc, -1, v143
	s_nop 1
	v_cndmask_b32_e32 v52, v205, v52, vcc
	v_cmp_lt_i32_e32 vcc, -1, v140
	s_nop 1
	v_cndmask_b32_e32 v51, v205, v51, vcc
	v_cmp_lt_i32_e32 vcc, -1, v141
	s_nop 1
	v_cndmask_b32_e32 v50, v205, v50, vcc
	v_cmp_lt_i32_e32 vcc, -1, v139
	s_nop 1
	v_cndmask_b32_e32 v49, v205, v49, vcc
	v_cmp_lt_i32_e32 vcc, -1, v138
	s_nop 1
	v_cndmask_b32_e32 v48, v205, v48, vcc
	v_cmp_lt_i32_e32 vcc, 31, v164
	s_nop 1
	v_cndmask_b32_e32 v47, v205, v47, vcc
	v_cmp_lt_i32_e32 vcc, 31, v165
	s_nop 1
	v_cndmask_b32_e32 v46, v205, v46, vcc
	v_cmp_lt_i32_e32 vcc, 31, v162
	s_nop 1
	v_cndmask_b32_e32 v45, v205, v45, vcc
	v_cmp_lt_i32_e32 vcc, 31, v163
	s_nop 1
	v_cndmask_b32_e32 v44, v205, v44, vcc
	v_cmp_lt_i32_e32 vcc, 31, v160
	s_nop 1
	v_cndmask_b32_e32 v43, v205, v43, vcc
	v_cmp_lt_i32_e32 vcc, 31, v161
	s_nop 1
	v_cndmask_b32_e32 v42, v205, v42, vcc
	v_cmp_lt_i32_e32 vcc, 31, v158
	s_nop 1
	v_cndmask_b32_e32 v41, v205, v41, vcc
	v_cmp_lt_i32_e32 vcc, 31, v159
	s_nop 1
	v_cndmask_b32_e32 v40, v205, v40, vcc
	v_cmp_lt_i32_e32 vcc, 31, v156
	s_nop 1
	v_cndmask_b32_e32 v39, v205, v39, vcc
	v_cmp_lt_i32_e32 vcc, 31, v157
	s_nop 1
	v_cndmask_b32_e32 v38, v205, v38, vcc
	v_cmp_lt_i32_e32 vcc, 31, v142
	s_nop 1
	v_cndmask_b32_e32 v37, v205, v37, vcc
	v_cmp_lt_i32_e32 vcc, 31, v143
	s_nop 1
	v_cndmask_b32_e32 v36, v205, v36, vcc
	v_cmp_lt_i32_e32 vcc, 31, v140
	s_nop 1
	v_cndmask_b32_e32 v35, v205, v35, vcc
	v_cmp_lt_i32_e32 vcc, 31, v141
	s_nop 1
	v_cndmask_b32_e32 v34, v205, v34, vcc
	v_cmp_lt_i32_e32 vcc, 31, v139
	s_nop 1
	v_cndmask_b32_e32 v33, v205, v33, vcc
	v_cmp_lt_i32_e32 vcc, 31, v138
	s_nop 1
	v_cndmask_b32_e32 v32, v205, v32, vcc
